# gb phase: loads of a thread's 3 tasks batched (one round trip); proj hook: NaN-canonicalising self-max removed
# speedup vs baseline: 1.0956x; 1.0009x over previous
.LBB0_1502:
	s_andn2_b64 vcc, exec, s[0:1]
	s_cbranch_vccnz .LBB0_1568
	s_waitcnt lgkmcnt(0)
	s_mov_b64 s[10:11], s[90:91]
	v_mov_b32_e32 v0, v195
	v_readlane_b32 s0, v253, 6
	s_nop 1
	v_add_u32_e32 v41, s0, v0
	s_mov_b32 s0, 0x60000
	v_cmp_gt_i32_e32 vcc, s0, v41
	s_and_saveexec_b64 s[0:1], vcc
	s_cbranch_execz .LBB0_1514
	s_load_dwordx2 s[4:5], s[10:11], 0xa8
	v_lshlrev_b32_e32 v42, 3, v41
	s_mov_b64 s[36:37], 0
	s_waitcnt lgkmcnt(0)
	s_add_u32 s10, s4, 0x39fe000
	s_addc_u32 s11, s5, 0
	s_add_u32 s16, s4, 0x59fe000
	s_addc_u32 s17, s5, 0
	s_add_u32 s18, s4, 0x8bfe400
	s_addc_u32 s19, s5, 0
	s_add_u32 s20, s4, 0xf22d400
	s_addc_u32 s21, s5, 0
	s_mov_b64 s[36:37], exec
	v_and_b32_e32 v50, 31, v41
	v_ashrrev_i32_e32 v52, 5, v41
	v_lshlrev_b32_e32 v50, 4, v50
	v_and_b32_e32 v54, 0x7ff, v52
	v_lshlrev_b32_e32 v53, 11, v52
	s_movk_i32 s4, 0x400
	v_add_u32_e32 v53, v53, v50
	v_cmp_gt_u32_e32 vcc, s4, v54
	v_sub_u32_e32 v55, 0x800, v54
	v_and_b32_e32 v57, 0xfffff800, v52
	v_lshrrev_b32_e32 v58, 11, v52
	v_cndmask_b32_e32 v55, v55, v54, vcc
	v_cndmask_b32_e64 v56, -1.0, 1.0, vcc
	v_cmp_ne_u32_e32 vcc, s4, v54
	s_nop 1
	s_and_b64 s[38:39], vcc, exec
	v_add_u32_e32 v57, v57, v55
	v_lshlrev_b32_e32 v57, 9, v57
	v_lshlrev_b32_e32 v58, 10, v58
	v_add_u32_e32 v57, v57, v50
	v_lshl_add_u32 v58, v50, 1, v58
	v_lshlrev_b32_e32 v59, 9, v52
	v_add_u32_e32 v59, v59, v50
	s_add_u32 s40, s18, 0x800000
	s_addc_u32 s41, s19, 0
	s_add_u32 s42, s18, 0x1000000
	s_addc_u32 s43, s19, 0
	global_load_dwordx4 v[60:63], v53, s[40:41]
	global_load_dwordx4 v[96:99], v53, s[42:43]
	global_load_dwordx4 v[132:135], v53, s[18:19]
	global_load_dwordx4 v[136:139], v59, s[16:17]
	s_mov_b64 s[4:5], s[10:11]
	s_mov_b64 exec, s[38:39]
	s_cbranch_execz .Lgb_noM
	global_load_dwordx4 v[64:67], v57, s[4:5]
	s_add_u32 s4, s4, 0x200000
	s_addc_u32 s5, s5, 0
	global_load_dwordx4 v[100:103], v57, s[4:5]
	s_add_u32 s4, s4, 0x200000
	s_addc_u32 s5, s5, 0
	global_load_dwordx4 v[68:71], v57, s[4:5]
	s_add_u32 s4, s4, 0x200000
	s_addc_u32 s5, s5, 0
	global_load_dwordx4 v[104:107], v57, s[4:5]
	s_add_u32 s4, s4, 0x200000
	s_addc_u32 s5, s5, 0
	global_load_dwordx4 v[72:75], v57, s[4:5]
	s_add_u32 s4, s4, 0x200000
	s_addc_u32 s5, s5, 0
	global_load_dwordx4 v[108:111], v57, s[4:5]
	s_add_u32 s4, s4, 0x200000
	s_addc_u32 s5, s5, 0
	global_load_dwordx4 v[76:79], v57, s[4:5]
	s_add_u32 s4, s4, 0x200000
	s_addc_u32 s5, s5, 0
	global_load_dwordx4 v[112:115], v57, s[4:5]
	s_add_u32 s4, s4, 0x200000
	s_addc_u32 s5, s5, 0
	global_load_dwordx4 v[80:83], v57, s[4:5]
	s_add_u32 s4, s4, 0x200000
	s_addc_u32 s5, s5, 0
	global_load_dwordx4 v[116:119], v57, s[4:5]
	s_add_u32 s4, s4, 0x200000
	s_addc_u32 s5, s5, 0
	global_load_dwordx4 v[84:87], v57, s[4:5]
	s_add_u32 s4, s4, 0x200000
	s_addc_u32 s5, s5, 0
	global_load_dwordx4 v[120:123], v57, s[4:5]
	s_add_u32 s4, s4, 0x200000
	s_addc_u32 s5, s5, 0
	global_load_dwordx4 v[88:91], v57, s[4:5]
	s_add_u32 s4, s4, 0x200000
	s_addc_u32 s5, s5, 0
	global_load_dwordx4 v[124:127], v57, s[4:5]
	s_add_u32 s4, s4, 0x200000
	s_addc_u32 s5, s5, 0
	global_load_dwordx4 v[92:95], v57, s[4:5]
	s_add_u32 s4, s4, 0x200000
	s_addc_u32 s5, s5, 0
	global_load_dwordx4 v[128:131], v57, s[4:5]
.Lgb_noM:
	s_andn2_b64 exec, s[36:37], s[38:39]
	s_cbranch_execz .Lgb_noY
	global_load_dwordx4 v[64:67], v58, s[20:21]
	global_load_dwordx4 v[68:71], v58, s[20:21] offset:16
	global_load_dwordx4 v[100:103], v58, s[20:21] offset:2048
	global_load_dwordx4 v[104:107], v58, s[20:21] offset:2064
.Lgb_noY:
	s_mov_b64 exec, s[36:37]
	s_waitcnt vmcnt(0)
	s_mov_b64 exec, s[38:39]
	s_cbranch_execz .Lgb_c0_noM
	v_lshlrev_b32_e32 v140, 16, v64
	v_and_b32_e32 v141, 0xffff0000, v64
	v_pk_add_f32 v[140:141], v[140:141], 0 op_sel_hi:[1,0]
	v_lshlrev_b32_e32 v148, 16, v68
	v_and_b32_e32 v149, 0xffff0000, v68
	v_pk_add_f32 v[140:141], v[140:141], v[148:149]
	v_lshlrev_b32_e32 v148, 16, v72
	v_and_b32_e32 v149, 0xffff0000, v72
	v_pk_add_f32 v[140:141], v[140:141], v[148:149]
	v_lshlrev_b32_e32 v148, 16, v76
	v_and_b32_e32 v149, 0xffff0000, v76
	v_pk_add_f32 v[140:141], v[140:141], v[148:149]
	v_lshlrev_b32_e32 v148, 16, v80
	v_and_b32_e32 v149, 0xffff0000, v80
	v_pk_fma_f32 v[140:141], v[56:57], v[148:149], v[140:141] op_sel_hi:[0,1,1]
	v_lshlrev_b32_e32 v148, 16, v84
	v_and_b32_e32 v149, 0xffff0000, v84
	v_pk_fma_f32 v[140:141], v[56:57], v[148:149], v[140:141] op_sel_hi:[0,1,1]
	v_lshlrev_b32_e32 v148, 16, v88
	v_and_b32_e32 v149, 0xffff0000, v88
	v_pk_fma_f32 v[140:141], v[56:57], v[148:149], v[140:141] op_sel_hi:[0,1,1]
	v_lshlrev_b32_e32 v148, 16, v92
	v_and_b32_e32 v149, 0xffff0000, v92
	v_pk_fma_f32 v[140:141], v[56:57], v[148:149], v[140:141] op_sel_hi:[0,1,1]
	v_lshlrev_b32_e32 v142, 16, v65
	v_and_b32_e32 v143, 0xffff0000, v65
	v_pk_add_f32 v[142:143], v[142:143], 0 op_sel_hi:[1,0]
	v_lshlrev_b32_e32 v148, 16, v69
	v_and_b32_e32 v149, 0xffff0000, v69
	v_pk_add_f32 v[142:143], v[142:143], v[148:149]
	v_lshlrev_b32_e32 v148, 16, v73
	v_and_b32_e32 v149, 0xffff0000, v73
	v_pk_add_f32 v[142:143], v[142:143], v[148:149]
	v_lshlrev_b32_e32 v148, 16, v77
	v_and_b32_e32 v149, 0xffff0000, v77
	v_pk_add_f32 v[142:143], v[142:143], v[148:149]
	v_lshlrev_b32_e32 v148, 16, v81
	v_and_b32_e32 v149, 0xffff0000, v81
	v_pk_fma_f32 v[142:143], v[56:57], v[148:149], v[142:143] op_sel_hi:[0,1,1]
	v_lshlrev_b32_e32 v148, 16, v85
	v_and_b32_e32 v149, 0xffff0000, v85
	v_pk_fma_f32 v[142:143], v[56:57], v[148:149], v[142:143] op_sel_hi:[0,1,1]
	v_lshlrev_b32_e32 v148, 16, v89
	v_and_b32_e32 v149, 0xffff0000, v89
	v_pk_fma_f32 v[142:143], v[56:57], v[148:149], v[142:143] op_sel_hi:[0,1,1]
	v_lshlrev_b32_e32 v148, 16, v93
	v_and_b32_e32 v149, 0xffff0000, v93
	v_pk_fma_f32 v[142:143], v[56:57], v[148:149], v[142:143] op_sel_hi:[0,1,1]
	v_lshlrev_b32_e32 v144, 16, v66
	v_and_b32_e32 v145, 0xffff0000, v66
	v_pk_add_f32 v[144:145], v[144:145], 0 op_sel_hi:[1,0]
	v_lshlrev_b32_e32 v148, 16, v70
	v_and_b32_e32 v149, 0xffff0000, v70
	v_pk_add_f32 v[144:145], v[144:145], v[148:149]
	v_lshlrev_b32_e32 v148, 16, v74
	v_and_b32_e32 v149, 0xffff0000, v74
	v_pk_add_f32 v[144:145], v[144:145], v[148:149]
	v_lshlrev_b32_e32 v148, 16, v78
	v_and_b32_e32 v149, 0xffff0000, v78
	v_pk_add_f32 v[144:145], v[144:145], v[148:149]
	v_lshlrev_b32_e32 v148, 16, v82
	v_and_b32_e32 v149, 0xffff0000, v82
	v_pk_fma_f32 v[144:145], v[56:57], v[148:149], v[144:145] op_sel_hi:[0,1,1]
	v_lshlrev_b32_e32 v148, 16, v86
	v_and_b32_e32 v149, 0xffff0000, v86
	v_pk_fma_f32 v[144:145], v[56:57], v[148:149], v[144:145] op_sel_hi:[0,1,1]
	v_lshlrev_b32_e32 v148, 16, v90
	v_and_b32_e32 v149, 0xffff0000, v90
	v_pk_fma_f32 v[144:145], v[56:57], v[148:149], v[144:145] op_sel_hi:[0,1,1]
	v_lshlrev_b32_e32 v148, 16, v94
	v_and_b32_e32 v149, 0xffff0000, v94
	v_pk_fma_f32 v[144:145], v[56:57], v[148:149], v[144:145] op_sel_hi:[0,1,1]
	v_lshlrev_b32_e32 v146, 16, v67
	v_and_b32_e32 v147, 0xffff0000, v67
	v_pk_add_f32 v[146:147], v[146:147], 0 op_sel_hi:[1,0]
	v_lshlrev_b32_e32 v148, 16, v71
	v_and_b32_e32 v149, 0xffff0000, v71
	v_pk_add_f32 v[146:147], v[146:147], v[148:149]
	v_lshlrev_b32_e32 v148, 16, v75
	v_and_b32_e32 v149, 0xffff0000, v75
	v_pk_add_f32 v[146:147], v[146:147], v[148:149]
	v_lshlrev_b32_e32 v148, 16, v79
	v_and_b32_e32 v149, 0xffff0000, v79
	v_pk_add_f32 v[146:147], v[146:147], v[148:149]
	v_lshlrev_b32_e32 v148, 16, v83
	v_and_b32_e32 v149, 0xffff0000, v83
	v_pk_fma_f32 v[146:147], v[56:57], v[148:149], v[146:147] op_sel_hi:[0,1,1]
	v_lshlrev_b32_e32 v148, 16, v87
	v_and_b32_e32 v149, 0xffff0000, v87
	v_pk_fma_f32 v[146:147], v[56:57], v[148:149], v[146:147] op_sel_hi:[0,1,1]
	v_lshlrev_b32_e32 v148, 16, v91
	v_and_b32_e32 v149, 0xffff0000, v91
	v_pk_fma_f32 v[146:147], v[56:57], v[148:149], v[146:147] op_sel_hi:[0,1,1]
	v_lshlrev_b32_e32 v148, 16, v95
	v_and_b32_e32 v149, 0xffff0000, v95
	v_pk_fma_f32 v[146:147], v[56:57], v[148:149], v[146:147] op_sel_hi:[0,1,1]
.Lgb_c0_noM:
	s_andn2_b64 exec, s[36:37], s[38:39]
	s_cbranch_execz .Lgb_c0_noY
	v_mov_b32_e32 v140, v64
	v_mov_b32_e32 v141, v65
	v_mov_b32_e32 v142, v66
	v_mov_b32_e32 v143, v67
	v_mov_b32_e32 v144, v68
	v_mov_b32_e32 v145, v69
	v_mov_b32_e32 v146, v70
	v_mov_b32_e32 v147, v71
.Lgb_c0_noY:
	s_mov_b64 exec, s[36:37]
	v_lshlrev_b32_e32 v148, 16, v60
	v_and_b32_e32 v149, 0xffff0000, v60
	v_pk_mul_f32 v[140:141], v[140:141], v[148:149]
	v_lshlrev_b32_e32 v148, 16, v61
	v_and_b32_e32 v149, 0xffff0000, v61
	v_pk_mul_f32 v[142:143], v[142:143], v[148:149]
	v_lshlrev_b32_e32 v148, 16, v62
	v_and_b32_e32 v149, 0xffff0000, v62
	v_pk_mul_f32 v[144:145], v[144:145], v[148:149]
	v_lshlrev_b32_e32 v148, 16, v63
	v_and_b32_e32 v149, 0xffff0000, v63
	v_pk_mul_f32 v[146:147], v[146:147], v[148:149]
	v_cvt_pk_bf16_f32 v60, v140, v141
	v_cvt_pk_bf16_f32 v61, v142, v143
	v_cvt_pk_bf16_f32 v62, v144, v145
	v_cvt_pk_bf16_f32 v63, v146, v147
	global_store_dwordx4 v53, v[60:63], s[40:41]
	s_mov_b64 exec, s[38:39]
	s_cbranch_execz .Lgb_c1_noM
	v_lshlrev_b32_e32 v140, 16, v100
	v_and_b32_e32 v141, 0xffff0000, v100
	v_pk_add_f32 v[140:141], v[140:141], 0 op_sel_hi:[1,0]
	v_lshlrev_b32_e32 v148, 16, v104
	v_and_b32_e32 v149, 0xffff0000, v104
	v_pk_add_f32 v[140:141], v[140:141], v[148:149]
	v_lshlrev_b32_e32 v148, 16, v108
	v_and_b32_e32 v149, 0xffff0000, v108
	v_pk_add_f32 v[140:141], v[140:141], v[148:149]
	v_lshlrev_b32_e32 v148, 16, v112
	v_and_b32_e32 v149, 0xffff0000, v112
	v_pk_add_f32 v[140:141], v[140:141], v[148:149]
	v_lshlrev_b32_e32 v148, 16, v116
	v_and_b32_e32 v149, 0xffff0000, v116
	v_pk_fma_f32 v[140:141], v[56:57], v[148:149], v[140:141] op_sel_hi:[0,1,1]
	v_lshlrev_b32_e32 v148, 16, v120
	v_and_b32_e32 v149, 0xffff0000, v120
	v_pk_fma_f32 v[140:141], v[56:57], v[148:149], v[140:141] op_sel_hi:[0,1,1]
	v_lshlrev_b32_e32 v148, 16, v124
	v_and_b32_e32 v149, 0xffff0000, v124
	v_pk_fma_f32 v[140:141], v[56:57], v[148:149], v[140:141] op_sel_hi:[0,1,1]
	v_lshlrev_b32_e32 v148, 16, v128
	v_and_b32_e32 v149, 0xffff0000, v128
	v_pk_fma_f32 v[140:141], v[56:57], v[148:149], v[140:141] op_sel_hi:[0,1,1]
	v_lshlrev_b32_e32 v142, 16, v101
	v_and_b32_e32 v143, 0xffff0000, v101
	v_pk_add_f32 v[142:143], v[142:143], 0 op_sel_hi:[1,0]
	v_lshlrev_b32_e32 v148, 16, v105
	v_and_b32_e32 v149, 0xffff0000, v105
	v_pk_add_f32 v[142:143], v[142:143], v[148:149]
	v_lshlrev_b32_e32 v148, 16, v109
	v_and_b32_e32 v149, 0xffff0000, v109
	v_pk_add_f32 v[142:143], v[142:143], v[148:149]
	v_lshlrev_b32_e32 v148, 16, v113
	v_and_b32_e32 v149, 0xffff0000, v113
	v_pk_add_f32 v[142:143], v[142:143], v[148:149]
	v_lshlrev_b32_e32 v148, 16, v117
	v_and_b32_e32 v149, 0xffff0000, v117
	v_pk_fma_f32 v[142:143], v[56:57], v[148:149], v[142:143] op_sel_hi:[0,1,1]
	v_lshlrev_b32_e32 v148, 16, v121
	v_and_b32_e32 v149, 0xffff0000, v121
	v_pk_fma_f32 v[142:143], v[56:57], v[148:149], v[142:143] op_sel_hi:[0,1,1]
	v_lshlrev_b32_e32 v148, 16, v125
	v_and_b32_e32 v149, 0xffff0000, v125
	v_pk_fma_f32 v[142:143], v[56:57], v[148:149], v[142:143] op_sel_hi:[0,1,1]
	v_lshlrev_b32_e32 v148, 16, v129
	v_and_b32_e32 v149, 0xffff0000, v129
	v_pk_fma_f32 v[142:143], v[56:57], v[148:149], v[142:143] op_sel_hi:[0,1,1]
	v_lshlrev_b32_e32 v144, 16, v102
	v_and_b32_e32 v145, 0xffff0000, v102
	v_pk_add_f32 v[144:145], v[144:145], 0 op_sel_hi:[1,0]
	v_lshlrev_b32_e32 v148, 16, v106
	v_and_b32_e32 v149, 0xffff0000, v106
	v_pk_add_f32 v[144:145], v[144:145], v[148:149]
	v_lshlrev_b32_e32 v148, 16, v110
	v_and_b32_e32 v149, 0xffff0000, v110
	v_pk_add_f32 v[144:145], v[144:145], v[148:149]
	v_lshlrev_b32_e32 v148, 16, v114
	v_and_b32_e32 v149, 0xffff0000, v114
	v_pk_add_f32 v[144:145], v[144:145], v[148:149]
	v_lshlrev_b32_e32 v148, 16, v118
	v_and_b32_e32 v149, 0xffff0000, v118
	v_pk_fma_f32 v[144:145], v[56:57], v[148:149], v[144:145] op_sel_hi:[0,1,1]
	v_lshlrev_b32_e32 v148, 16, v122
	v_and_b32_e32 v149, 0xffff0000, v122
	v_pk_fma_f32 v[144:145], v[56:57], v[148:149], v[144:145] op_sel_hi:[0,1,1]
	v_lshlrev_b32_e32 v148, 16, v126
	v_and_b32_e32 v149, 0xffff0000, v126
	v_pk_fma_f32 v[144:145], v[56:57], v[148:149], v[144:145] op_sel_hi:[0,1,1]
	v_lshlrev_b32_e32 v148, 16, v130
	v_and_b32_e32 v149, 0xffff0000, v130
	v_pk_fma_f32 v[144:145], v[56:57], v[148:149], v[144:145] op_sel_hi:[0,1,1]
	v_lshlrev_b32_e32 v146, 16, v103
	v_and_b32_e32 v147, 0xffff0000, v103
	v_pk_add_f32 v[146:147], v[146:147], 0 op_sel_hi:[1,0]
	v_lshlrev_b32_e32 v148, 16, v107
	v_and_b32_e32 v149, 0xffff0000, v107
	v_pk_add_f32 v[146:147], v[146:147], v[148:149]
	v_lshlrev_b32_e32 v148, 16, v111
	v_and_b32_e32 v149, 0xffff0000, v111
	v_pk_add_f32 v[146:147], v[146:147], v[148:149]
	v_lshlrev_b32_e32 v148, 16, v115
	v_and_b32_e32 v149, 0xffff0000, v115
	v_pk_add_f32 v[146:147], v[146:147], v[148:149]
	v_lshlrev_b32_e32 v148, 16, v119
	v_and_b32_e32 v149, 0xffff0000, v119
	v_pk_fma_f32 v[146:147], v[56:57], v[148:149], v[146:147] op_sel_hi:[0,1,1]
	v_lshlrev_b32_e32 v148, 16, v123
	v_and_b32_e32 v149, 0xffff0000, v123
	v_pk_fma_f32 v[146:147], v[56:57], v[148:149], v[146:147] op_sel_hi:[0,1,1]
	v_lshlrev_b32_e32 v148, 16, v127
	v_and_b32_e32 v149, 0xffff0000, v127
	v_pk_fma_f32 v[146:147], v[56:57], v[148:149], v[146:147] op_sel_hi:[0,1,1]
	v_lshlrev_b32_e32 v148, 16, v131
	v_and_b32_e32 v149, 0xffff0000, v131
	v_pk_fma_f32 v[146:147], v[56:57], v[148:149], v[146:147] op_sel_hi:[0,1,1]
.Lgb_c1_noM:
	s_andn2_b64 exec, s[36:37], s[38:39]
	s_cbranch_execz .Lgb_c1_noY
	v_mov_b32_e32 v140, v100
	v_mov_b32_e32 v141, v101
	v_mov_b32_e32 v142, v102
	v_mov_b32_e32 v143, v103
	v_mov_b32_e32 v144, v104
	v_mov_b32_e32 v145, v105
	v_mov_b32_e32 v146, v106
	v_mov_b32_e32 v147, v107
.Lgb_c1_noY:
	s_mov_b64 exec, s[36:37]
	v_lshlrev_b32_e32 v148, 16, v96
	v_and_b32_e32 v149, 0xffff0000, v96
	v_pk_mul_f32 v[140:141], v[140:141], v[148:149]
	v_lshlrev_b32_e32 v148, 16, v97
	v_and_b32_e32 v149, 0xffff0000, v97
	v_pk_mul_f32 v[142:143], v[142:143], v[148:149]
	v_lshlrev_b32_e32 v148, 16, v98
	v_and_b32_e32 v149, 0xffff0000, v98
	v_pk_mul_f32 v[144:145], v[144:145], v[148:149]
	v_lshlrev_b32_e32 v148, 16, v99
	v_and_b32_e32 v149, 0xffff0000, v99
	v_pk_mul_f32 v[146:147], v[146:147], v[148:149]
	v_cvt_pk_bf16_f32 v96, v140, v141
	v_cvt_pk_bf16_f32 v97, v142, v143
	v_cvt_pk_bf16_f32 v98, v144, v145
	v_cvt_pk_bf16_f32 v99, v146, v147
	global_store_dwordx4 v53, v[96:99], s[42:43]
	v_lshlrev_b32_e32 v140, 16, v136
	v_and_b32_e32 v141, 0xffff0000, v136
	v_lshlrev_b32_e32 v142, 16, v137
	v_and_b32_e32 v143, 0xffff0000, v137
	v_lshlrev_b32_e32 v144, 16, v138
	v_and_b32_e32 v145, 0xffff0000, v138
	v_lshlrev_b32_e32 v146, 16, v139
	v_and_b32_e32 v147, 0xffff0000, v139
	v_lshlrev_b32_e32 v148, 16, v132
	v_and_b32_e32 v149, 0xffff0000, v132
	v_pk_mul_f32 v[140:141], v[140:141], v[148:149]
	v_lshlrev_b32_e32 v148, 16, v133
	v_and_b32_e32 v149, 0xffff0000, v133
	v_pk_mul_f32 v[142:143], v[142:143], v[148:149]
	v_lshlrev_b32_e32 v148, 16, v134
	v_and_b32_e32 v149, 0xffff0000, v134
	v_pk_mul_f32 v[144:145], v[144:145], v[148:149]
	v_lshlrev_b32_e32 v148, 16, v135
	v_and_b32_e32 v149, 0xffff0000, v135
	v_pk_mul_f32 v[146:147], v[146:147], v[148:149]
	v_cvt_pk_bf16_f32 v132, v140, v141
	v_cvt_pk_bf16_f32 v133, v142, v143
	v_cvt_pk_bf16_f32 v134, v144, v145
	v_cvt_pk_bf16_f32 v135, v146, v147
	global_store_dwordx4 v53, v[132:135], s[18:19]

.LBB0_1581:
	s_add_i32 s53, s53, 2
	s_and_b32 s10, s53, 10
	s_cmp_lg_u32 s10, 8
	s_cbranch_scc1 .LBB0_1580
	v_mov_b32_e32 v128, v206
	s_cmpk_eq_i32 s62, 0x400
	v_and_b32_e32 v129, 15, v128
	v_ashrrev_i32_e32 v128, 4, v128
	s_mov_b32 s16, s65
	s_mov_b32 s17, s79
	s_cselect_b32 s10, 0, 0x1800000
	s_add_u32 s10, s4, s10
	s_addc_u32 s11, s5, 0
	s_lshl_b32 s17, s17, 10
	s_lshl_b32 s16, s16, 12
	v_lshlrev_b32_e32 v128, 4, v128
	s_add_i32 s16, s16, s17
	v_add3_u32 v128, s16, v129, v128
	v_ashrrev_i32_e32 v129, 31, v128
	v_lshl_add_u64 v[160:161], v[128:129], 4, s[10:11]
	global_load_dwordx4 v[152:155], v[160:161], off nt
	v_add_co_u32_e32 v128, vcc, s73, v160
	s_mov_b32 s10, 0x1801000
	s_nop 0
	v_addc_co_u32_e32 v129, vcc, 0, v161, vcc
	v_add_co_u32_e32 v132, vcc, s10, v160
	s_mov_b32 s10, 0x1802000
	s_nop 0
	v_addc_co_u32_e32 v133, vcc, 0, v161, vcc
	global_load_dwordx4 v[156:159], v[132:133], off offset:-4096
	global_load_dwordx4 v[164:167], v[160:161], off offset:1024 nt
	global_load_dwordx4 v[168:171], v[128:129], off offset:1024
	global_load_dwordx4 v[172:175], v[160:161], off offset:2048 nt
	global_load_dwordx4 v[176:179], v[128:129], off offset:2048
	global_load_dwordx4 v[180:183], v[160:161], off offset:3072 nt
	global_load_dwordx4 v[184:187], v[128:129], off offset:3072
	v_add_co_u32_e32 v128, vcc, s33, v160
	s_waitcnt vmcnt(0)
	v_lshlrev_b32_e32 v226, 16, v152
	v_and_b32_e32 v227, 0xffff0000, v152
	v_addc_co_u32_e32 v129, vcc, 0, v161, vcc
	v_add_co_u32_e32 v162, vcc, s35, v160
	v_lshlrev_b32_e32 v209, 16, v156
	v_and_b32_e32 v156, 0xffff0000, v156
	v_lshlrev_b32_e32 v152, 16, v157
	v_max_f32_e32 v156, 0xda24260, v156
	v_max_f32_e32 v152, 0xda24260, v152
	v_rcp_f32_e32 v225, v156
	v_rcp_f32_e32 v156, v152
	v_and_b32_e32 v152, 0xffff0000, v157
	v_max_f32_e32 v152, 0xda24260, v152
	v_rcp_f32_e32 v157, v152
	v_lshlrev_b32_e32 v152, 16, v153
	v_and_b32_e32 v153, 0xffff0000, v153
	v_addc_co_u32_e32 v163, vcc, 0, v161, vcc
	v_pk_mul_f32 v[152:153], v[156:157], v[152:153]
	v_lshlrev_b32_e32 v156, 16, v154
	v_pk_mul_f32 v[126:127], v[126:127], v[152:153]
	v_lshlrev_b32_e32 v152, 16, v158
	v_and_b32_e32 v153, 0xffff0000, v158
	v_max_f32_e32 v152, 0xda24260, v152
	v_max_f32_e32 v153, 0xda24260, v153
	v_rcp_f32_e32 v152, v152
	v_rcp_f32_e32 v153, v153
	v_and_b32_e32 v157, 0xffff0000, v154
	v_lshlrev_b32_e32 v154, 16, v155
	v_and_b32_e32 v155, 0xffff0000, v155
	v_pk_mul_f32 v[152:153], v[152:153], v[156:157]
	global_load_dwordx4 v[188:191], v[162:163], off offset:-4096 nt
	global_load_dwordx4 v[210:213], v[132:133], off
	global_load_dwordx4 v[144:147], v[128:129], off offset:1024 nt
	global_load_dwordx4 v[148:151], v[132:133], off offset:1024
	global_load_dwordx4 v[136:139], v[128:129], off offset:2048 nt
	global_load_dwordx4 v[140:143], v[132:133], off offset:2048
	s_nop 0
	global_load_dwordx4 v[128:131], v[128:129], off offset:3072 nt
	s_nop 0
	global_load_dwordx4 v[132:135], v[132:133], off offset:3072
	v_pk_mul_f32 v[120:121], v[120:121], v[152:153]
	v_lshlrev_b32_e32 v152, 16, v159
	v_and_b32_e32 v153, 0xffff0000, v159
	v_max_f32_e32 v152, 0xda24260, v152
	v_max_f32_e32 v153, 0xda24260, v153
	v_rcp_f32_e32 v152, v152
	v_rcp_f32_e32 v153, v153
	v_max_f32_e32 v209, 0xda24260, v209
	v_rcp_f32_e32 v224, v209
	v_pk_mul_f32 v[152:153], v[152:153], v[154:155]
	v_lshlrev_b32_e32 v154, 16, v164
	v_pk_mul_f32 v[122:123], v[122:123], v[152:153]
	v_lshlrev_b32_e32 v152, 16, v168
	v_and_b32_e32 v153, 0xffff0000, v168
	v_max_f32_e32 v152, 0xda24260, v152
	v_max_f32_e32 v153, 0xda24260, v153
	v_rcp_f32_e32 v152, v152
	v_rcp_f32_e32 v153, v153
	v_and_b32_e32 v155, 0xffff0000, v164
	v_pk_mul_f32 v[224:225], v[224:225], v[226:227]
	v_pk_mul_f32 v[152:153], v[152:153], v[154:155]
	s_nop 0
	v_pk_mul_f32 v[116:117], v[116:117], v[152:153]
	v_lshlrev_b32_e32 v152, 16, v169
	v_and_b32_e32 v153, 0xffff0000, v169
	v_max_f32_e32 v152, 0xda24260, v152
	v_max_f32_e32 v153, 0xda24260, v153
	v_rcp_f32_e32 v152, v152
	v_rcp_f32_e32 v153, v153
	v_lshlrev_b32_e32 v154, 16, v165
	v_and_b32_e32 v155, 0xffff0000, v165
	v_pk_mul_f32 v[124:125], v[124:125], v[224:225]
	v_pk_mul_f32 v[152:153], v[152:153], v[154:155]
	v_lshlrev_b32_e32 v154, 16, v166
	v_pk_mul_f32 v[118:119], v[118:119], v[152:153]
	v_lshlrev_b32_e32 v152, 16, v170
	v_and_b32_e32 v153, 0xffff0000, v170
	v_max_f32_e32 v152, 0xda24260, v152
	v_max_f32_e32 v153, 0xda24260, v153
	v_rcp_f32_e32 v152, v152
	v_rcp_f32_e32 v153, v153
	v_and_b32_e32 v155, 0xffff0000, v166
	v_pk_mul_f32 v[152:153], v[152:153], v[154:155]
	s_nop 0
	v_pk_mul_f32 v[112:113], v[112:113], v[152:153]
	v_lshlrev_b32_e32 v152, 16, v171
	v_and_b32_e32 v153, 0xffff0000, v171
	v_max_f32_e32 v152, 0xda24260, v152
	v_max_f32_e32 v153, 0xda24260, v153
	v_rcp_f32_e32 v152, v152
	v_rcp_f32_e32 v153, v153
	v_lshlrev_b32_e32 v154, 16, v167
	v_and_b32_e32 v155, 0xffff0000, v167
	v_pk_mul_f32 v[152:153], v[152:153], v[154:155]
	s_nop 0
	v_pk_mul_f32 v[114:115], v[114:115], v[152:153]
	v_lshlrev_b32_e32 v152, 16, v176
	v_and_b32_e32 v153, 0xffff0000, v176
	v_max_f32_e32 v152, 0xda24260, v152
	v_max_f32_e32 v153, 0xda24260, v153
	v_rcp_f32_e32 v152, v152
	v_rcp_f32_e32 v153, v153
	v_lshlrev_b32_e32 v154, 16, v172
	v_and_b32_e32 v155, 0xffff0000, v172
	v_pk_mul_f32 v[152:153], v[152:153], v[154:155]
	s_nop 0
	v_pk_mul_f32 v[108:109], v[108:109], v[152:153]
	v_lshlrev_b32_e32 v152, 16, v177
	v_and_b32_e32 v153, 0xffff0000, v177
	v_max_f32_e32 v152, 0xda24260, v152
	v_max_f32_e32 v153, 0xda24260, v153
	v_rcp_f32_e32 v152, v152
	v_rcp_f32_e32 v153, v153
	v_lshlrev_b32_e32 v154, 16, v173
	v_and_b32_e32 v155, 0xffff0000, v173
	v_pk_mul_f32 v[152:153], v[152:153], v[154:155]
	s_nop 0
	v_pk_mul_f32 v[110:111], v[110:111], v[152:153]
	v_lshlrev_b32_e32 v152, 16, v178
	v_and_b32_e32 v153, 0xffff0000, v178
	v_max_f32_e32 v152, 0xda24260, v152
	v_max_f32_e32 v153, 0xda24260, v153
	v_rcp_f32_e32 v152, v152
	v_rcp_f32_e32 v153, v153
	v_lshlrev_b32_e32 v154, 16, v174
	v_and_b32_e32 v155, 0xffff0000, v174
	v_pk_mul_f32 v[152:153], v[152:153], v[154:155]
	s_nop 0
	v_pk_mul_f32 v[104:105], v[104:105], v[152:153]
	v_lshlrev_b32_e32 v152, 16, v179
	v_and_b32_e32 v153, 0xffff0000, v179
	v_max_f32_e32 v152, 0xda24260, v152
	v_max_f32_e32 v153, 0xda24260, v153
	v_rcp_f32_e32 v152, v152
	v_rcp_f32_e32 v153, v153
	v_lshlrev_b32_e32 v154, 16, v175
	v_and_b32_e32 v155, 0xffff0000, v175
	v_pk_mul_f32 v[152:153], v[152:153], v[154:155]
	s_nop 0
	v_pk_mul_f32 v[106:107], v[106:107], v[152:153]
	v_lshlrev_b32_e32 v152, 16, v184
	v_and_b32_e32 v153, 0xffff0000, v184
	v_max_f32_e32 v152, 0xda24260, v152
	v_max_f32_e32 v153, 0xda24260, v153
	v_rcp_f32_e32 v152, v152
	v_rcp_f32_e32 v153, v153
	v_lshlrev_b32_e32 v154, 16, v180
	v_and_b32_e32 v155, 0xffff0000, v180
	v_pk_mul_f32 v[152:153], v[152:153], v[154:155]
	s_nop 0
	v_pk_mul_f32 v[100:101], v[100:101], v[152:153]
	v_lshlrev_b32_e32 v152, 16, v185
	v_and_b32_e32 v153, 0xffff0000, v185
	v_max_f32_e32 v152, 0xda24260, v152
	v_max_f32_e32 v153, 0xda24260, v153
	v_rcp_f32_e32 v152, v152
	v_rcp_f32_e32 v153, v153
	v_lshlrev_b32_e32 v154, 16, v181
	v_and_b32_e32 v155, 0xffff0000, v181
	v_pk_mul_f32 v[152:153], v[152:153], v[154:155]
	s_nop 0
	v_pk_mul_f32 v[102:103], v[102:103], v[152:153]
	v_lshlrev_b32_e32 v152, 16, v186
	v_and_b32_e32 v153, 0xffff0000, v186
	v_max_f32_e32 v152, 0xda24260, v152
	v_max_f32_e32 v153, 0xda24260, v153
	v_rcp_f32_e32 v152, v152
	v_rcp_f32_e32 v153, v153
	v_lshlrev_b32_e32 v154, 16, v182
	v_and_b32_e32 v155, 0xffff0000, v182
	v_pk_mul_f32 v[152:153], v[152:153], v[154:155]
	s_nop 0
	v_pk_mul_f32 v[92:93], v[92:93], v[152:153]
	v_lshlrev_b32_e32 v152, 16, v187
	v_and_b32_e32 v153, 0xffff0000, v187
	v_max_f32_e32 v152, 0xda24260, v152
	v_max_f32_e32 v153, 0xda24260, v153
	v_rcp_f32_e32 v152, v152
	v_rcp_f32_e32 v153, v153
	v_lshlrev_b32_e32 v154, 16, v183
	v_and_b32_e32 v155, 0xffff0000, v183
	v_pk_mul_f32 v[152:153], v[152:153], v[154:155]
	s_nop 0
	v_pk_mul_f32 v[94:95], v[94:95], v[152:153]
	s_waitcnt vmcnt(0)
	v_lshlrev_b32_e32 v152, 16, v210
	v_and_b32_e32 v153, 0xffff0000, v210
	v_max_f32_e32 v152, 0xda24260, v152
	v_max_f32_e32 v153, 0xda24260, v153
	v_rcp_f32_e32 v152, v152
	v_rcp_f32_e32 v153, v153
	v_lshlrev_b32_e32 v154, 16, v188
	v_and_b32_e32 v155, 0xffff0000, v188
	v_pk_mul_f32 v[152:153], v[152:153], v[154:155]
	s_nop 0
	v_pk_mul_f32 v[96:97], v[96:97], v[152:153]
	v_lshlrev_b32_e32 v152, 16, v211
	v_and_b32_e32 v153, 0xffff0000, v211
	v_max_f32_e32 v152, 0xda24260, v152
	v_max_f32_e32 v153, 0xda24260, v153
	v_rcp_f32_e32 v152, v152
	v_rcp_f32_e32 v153, v153
	v_lshlrev_b32_e32 v154, 16, v189
	v_and_b32_e32 v155, 0xffff0000, v189
	v_pk_mul_f32 v[152:153], v[152:153], v[154:155]
	s_nop 0
	v_pk_mul_f32 v[98:99], v[98:99], v[152:153]
	v_lshlrev_b32_e32 v152, 16, v212
	v_and_b32_e32 v153, 0xffff0000, v212
	v_max_f32_e32 v152, 0xda24260, v152
	v_max_f32_e32 v153, 0xda24260, v153
	v_rcp_f32_e32 v152, v152
	v_rcp_f32_e32 v153, v153
	v_lshlrev_b32_e32 v154, 16, v190
	v_and_b32_e32 v155, 0xffff0000, v190
	v_pk_mul_f32 v[152:153], v[152:153], v[154:155]
	s_nop 0
	v_pk_mul_f32 v[88:89], v[88:89], v[152:153]
	v_lshlrev_b32_e32 v152, 16, v213
	v_and_b32_e32 v153, 0xffff0000, v213
	v_max_f32_e32 v152, 0xda24260, v152
	v_max_f32_e32 v153, 0xda24260, v153
	v_rcp_f32_e32 v152, v152
	v_rcp_f32_e32 v153, v153
	v_lshlrev_b32_e32 v154, 16, v191
	v_and_b32_e32 v155, 0xffff0000, v191
	v_pk_mul_f32 v[152:153], v[152:153], v[154:155]
	s_nop 0
	v_pk_mul_f32 v[90:91], v[90:91], v[152:153]
	v_lshlrev_b32_e32 v152, 16, v148
	v_and_b32_e32 v148, 0xffff0000, v148
	v_lshlrev_b32_e32 v154, 16, v144
	v_and_b32_e32 v155, 0xffff0000, v144
	v_lshlrev_b32_e32 v144, 16, v149
	v_max_f32_e32 v148, 0xda24260, v148
	v_max_f32_e32 v144, 0xda24260, v144
	v_rcp_f32_e32 v153, v148
	v_rcp_f32_e32 v148, v144
	v_and_b32_e32 v144, 0xffff0000, v149
	v_max_f32_e32 v144, 0xda24260, v144
	v_rcp_f32_e32 v149, v144
	v_lshlrev_b32_e32 v144, 16, v145
	v_and_b32_e32 v145, 0xffff0000, v145
	v_pk_mul_f32 v[144:145], v[148:149], v[144:145]
	v_lshlrev_b32_e32 v148, 16, v146
	v_pk_mul_f32 v[86:87], v[86:87], v[144:145]
	v_lshlrev_b32_e32 v144, 16, v150
	v_and_b32_e32 v145, 0xffff0000, v150
	v_max_f32_e32 v144, 0xda24260, v144
	v_max_f32_e32 v145, 0xda24260, v145
	v_rcp_f32_e32 v144, v144
	v_rcp_f32_e32 v145, v145
	v_and_b32_e32 v149, 0xffff0000, v146
	v_lshlrev_b32_e32 v146, 16, v147
	v_and_b32_e32 v147, 0xffff0000, v147
	v_pk_mul_f32 v[144:145], v[144:145], v[148:149]
	v_max_f32_e32 v152, 0xda24260, v152
	v_pk_mul_f32 v[76:77], v[76:77], v[144:145]
	v_lshlrev_b32_e32 v144, 16, v151
	v_and_b32_e32 v145, 0xffff0000, v151
	v_max_f32_e32 v144, 0xda24260, v144
	v_max_f32_e32 v145, 0xda24260, v145
	v_rcp_f32_e32 v144, v144
	v_rcp_f32_e32 v145, v145
	v_rcp_f32_e32 v152, v152
	v_pk_mul_f32 v[144:145], v[144:145], v[146:147]
	s_nop 0
	v_pk_mul_f32 v[78:79], v[78:79], v[144:145]
	v_lshlrev_b32_e32 v144, 16, v140
	v_and_b32_e32 v140, 0xffff0000, v140
	v_lshlrev_b32_e32 v146, 16, v136
	v_and_b32_e32 v147, 0xffff0000, v136
	v_lshlrev_b32_e32 v136, 16, v141
	v_max_f32_e32 v140, 0xda24260, v140
	v_max_f32_e32 v136, 0xda24260, v136
	v_rcp_f32_e32 v145, v140
	v_rcp_f32_e32 v140, v136
	v_and_b32_e32 v136, 0xffff0000, v141
	v_max_f32_e32 v136, 0xda24260, v136
	v_rcp_f32_e32 v141, v136
	v_lshlrev_b32_e32 v136, 16, v137
	v_and_b32_e32 v137, 0xffff0000, v137
	v_pk_mul_f32 v[152:153], v[152:153], v[154:155]
	v_pk_mul_f32 v[136:137], v[140:141], v[136:137]
	v_lshlrev_b32_e32 v140, 16, v138
	v_pk_mul_f32 v[82:83], v[82:83], v[136:137]
	v_lshlrev_b32_e32 v136, 16, v142
	v_and_b32_e32 v137, 0xffff0000, v142
	v_max_f32_e32 v136, 0xda24260, v136
	v_max_f32_e32 v137, 0xda24260, v137
	v_rcp_f32_e32 v136, v136
	v_rcp_f32_e32 v137, v137
	v_and_b32_e32 v141, 0xffff0000, v138
	v_lshlrev_b32_e32 v138, 16, v139
	v_and_b32_e32 v139, 0xffff0000, v139
	v_pk_mul_f32 v[136:137], v[136:137], v[140:141]
	v_pk_mul_f32 v[72:73], v[72:73], v[136:137]
	v_lshlrev_b32_e32 v136, 16, v143
	v_and_b32_e32 v137, 0xffff0000, v143
	v_max_f32_e32 v136, 0xda24260, v136
	v_max_f32_e32 v137, 0xda24260, v137
	v_rcp_f32_e32 v136, v136
	v_rcp_f32_e32 v137, v137
	v_pk_mul_f32 v[84:85], v[84:85], v[152:153]
	v_max_f32_e32 v144, 0xda24260, v144
	global_load_dwordx4 v[152:155], v[162:163], off nt
	v_pk_mul_f32 v[136:137], v[136:137], v[138:139]
	v_lshlrev_b32_e32 v138, 16, v128
	v_pk_mul_f32 v[74:75], v[74:75], v[136:137]
	v_lshlrev_b32_e32 v136, 16, v132
	v_and_b32_e32 v132, 0xffff0000, v132
	v_and_b32_e32 v139, 0xffff0000, v128
	v_lshlrev_b32_e32 v128, 16, v133
	v_max_f32_e32 v132, 0xda24260, v132
	v_max_f32_e32 v128, 0xda24260, v128
	v_rcp_f32_e32 v137, v132
	v_rcp_f32_e32 v132, v128
	v_and_b32_e32 v128, 0xffff0000, v133
	v_max_f32_e32 v128, 0xda24260, v128
	v_rcp_f32_e32 v133, v128
	v_lshlrev_b32_e32 v128, 16, v129
	v_and_b32_e32 v129, 0xffff0000, v129
	v_pk_mul_f32 v[128:129], v[132:133], v[128:129]
	v_lshlrev_b32_e32 v132, 16, v130
	v_pk_mul_f32 v[70:71], v[70:71], v[128:129]
	v_lshlrev_b32_e32 v128, 16, v134
	v_and_b32_e32 v129, 0xffff0000, v134
	v_max_f32_e32 v128, 0xda24260, v128
	v_max_f32_e32 v129, 0xda24260, v129
	v_rcp_f32_e32 v128, v128
	v_rcp_f32_e32 v129, v129
	v_and_b32_e32 v133, 0xffff0000, v130
	v_max_f32_e32 v136, 0xda24260, v136
	v_rcp_f32_e32 v144, v144
	v_pk_mul_f32 v[128:129], v[128:129], v[132:133]
	v_rcp_f32_e32 v136, v136
	v_pk_mul_f32 v[64:65], v[64:65], v[128:129]
	v_lshlrev_b32_e32 v128, 16, v135
	v_and_b32_e32 v129, 0xffff0000, v135
	v_max_f32_e32 v128, 0xda24260, v128
	v_max_f32_e32 v129, 0xda24260, v129
	v_rcp_f32_e32 v128, v128
	v_rcp_f32_e32 v129, v129
	v_add_co_u32_e32 v132, vcc, s10, v160
	s_mov_b32 s10, 0x1803000
	s_nop 0
	v_addc_co_u32_e32 v133, vcc, 0, v161, vcc
	v_lshlrev_b32_e32 v130, 16, v131
	v_and_b32_e32 v131, 0xffff0000, v131
	v_add_co_u32_e32 v164, vcc, s10, v160
	v_pk_mul_f32 v[144:145], v[144:145], v[146:147]
	v_pk_mul_f32 v[136:137], v[136:137], v[138:139]
	v_pk_mul_f32 v[128:129], v[128:129], v[130:131]
	v_addc_co_u32_e32 v165, vcc, 0, v161, vcc
	v_pk_mul_f32 v[80:81], v[80:81], v[144:145]
	v_pk_mul_f32 v[68:69], v[68:69], v[136:137]
	v_pk_mul_f32 v[66:67], v[66:67], v[128:129]
	global_load_dwordx4 v[156:159], v[164:165], off offset:-4096
	global_load_dwordx4 v[144:147], v[162:163], off offset:1024 nt
	global_load_dwordx4 v[148:151], v[132:133], off offset:1024
	global_load_dwordx4 v[136:139], v[162:163], off offset:2048 nt
	global_load_dwordx4 v[140:143], v[132:133], off offset:2048
	global_load_dwordx4 v[128:131], v[162:163], off offset:3072 nt
	s_nop 0
	global_load_dwordx4 v[132:135], v[132:133], off offset:3072
	v_add_co_u32_e32 v160, vcc, s34, v160
	s_waitcnt vmcnt(0)
	v_lshlrev_b32_e32 v212, 16, v152
	v_and_b32_e32 v213, 0xffff0000, v152
	v_addc_co_u32_e32 v161, vcc, 0, v161, vcc
	global_load_dwordx4 v[184:187], v[160:161], off nt
	global_load_dwordx4 v[188:191], v[164:165], off
	global_load_dwordx4 v[176:179], v[160:161], off offset:1024 nt
	global_load_dwordx4 v[180:183], v[164:165], off offset:1024
	global_load_dwordx4 v[168:171], v[160:161], off offset:2048 nt
	global_load_dwordx4 v[172:175], v[164:165], off offset:2048
	s_nop 0
	global_load_dwordx4 v[160:163], v[160:161], off offset:3072 nt
	s_nop 0
	global_load_dwordx4 v[164:167], v[164:165], off offset:3072
	v_lshlrev_b32_e32 v209, 16, v156
	v_and_b32_e32 v156, 0xffff0000, v156
	v_lshlrev_b32_e32 v152, 16, v157
	v_max_f32_e32 v156, 0xda24260, v156
	v_max_f32_e32 v152, 0xda24260, v152
	v_rcp_f32_e32 v211, v156
	v_rcp_f32_e32 v156, v152
	v_and_b32_e32 v152, 0xffff0000, v157
	v_max_f32_e32 v152, 0xda24260, v152
	v_rcp_f32_e32 v157, v152
	v_lshlrev_b32_e32 v152, 16, v153
	v_and_b32_e32 v153, 0xffff0000, v153
	v_pk_mul_f32 v[152:153], v[156:157], v[152:153]
	v_lshlrev_b32_e32 v156, 16, v154
	v_pk_mul_f32 v[62:63], v[62:63], v[152:153]
	v_lshlrev_b32_e32 v152, 16, v158
	v_and_b32_e32 v153, 0xffff0000, v158
	v_max_f32_e32 v152, 0xda24260, v152
	v_max_f32_e32 v153, 0xda24260, v153
	v_rcp_f32_e32 v152, v152
	v_rcp_f32_e32 v153, v153
	v_and_b32_e32 v157, 0xffff0000, v154
	v_lshlrev_b32_e32 v154, 16, v155
	v_and_b32_e32 v155, 0xffff0000, v155
	v_pk_mul_f32 v[152:153], v[152:153], v[156:157]
	v_max_f32_e32 v209, 0xda24260, v209
	v_pk_mul_f32 v[56:57], v[56:57], v[152:153]
	v_lshlrev_b32_e32 v152, 16, v159
	v_and_b32_e32 v153, 0xffff0000, v159
	v_max_f32_e32 v152, 0xda24260, v152
	v_max_f32_e32 v153, 0xda24260, v153
	v_rcp_f32_e32 v152, v152
	v_rcp_f32_e32 v153, v153
	v_rcp_f32_e32 v210, v209
	v_pk_mul_f32 v[152:153], v[152:153], v[154:155]
	s_nop 0
	v_pk_mul_f32 v[58:59], v[58:59], v[152:153]
	v_lshlrev_b32_e32 v152, 16, v148
	v_and_b32_e32 v148, 0xffff0000, v148
	v_lshlrev_b32_e32 v154, 16, v144
	v_and_b32_e32 v155, 0xffff0000, v144
	v_lshlrev_b32_e32 v144, 16, v149
	v_max_f32_e32 v148, 0xda24260, v148
	v_max_f32_e32 v144, 0xda24260, v144
	v_rcp_f32_e32 v153, v148
	v_rcp_f32_e32 v148, v144
	v_and_b32_e32 v144, 0xffff0000, v149
	v_max_f32_e32 v144, 0xda24260, v144
	v_rcp_f32_e32 v149, v144
	v_lshlrev_b32_e32 v144, 16, v145
	v_and_b32_e32 v145, 0xffff0000, v145
	v_pk_mul_f32 v[144:145], v[148:149], v[144:145]
	v_lshlrev_b32_e32 v148, 16, v146
	v_pk_mul_f32 v[54:55], v[54:55], v[144:145]
	v_lshlrev_b32_e32 v144, 16, v150
	v_and_b32_e32 v145, 0xffff0000, v150
	v_max_f32_e32 v144, 0xda24260, v144
	v_max_f32_e32 v145, 0xda24260, v145
	v_rcp_f32_e32 v144, v144
	v_rcp_f32_e32 v145, v145
	v_and_b32_e32 v149, 0xffff0000, v146
	v_lshlrev_b32_e32 v146, 16, v147
	v_and_b32_e32 v147, 0xffff0000, v147
	v_pk_mul_f32 v[144:145], v[144:145], v[148:149]
	v_max_f32_e32 v152, 0xda24260, v152
	v_pk_mul_f32 v[44:45], v[44:45], v[144:145]
	v_lshlrev_b32_e32 v144, 16, v151
	v_and_b32_e32 v145, 0xffff0000, v151
	v_max_f32_e32 v144, 0xda24260, v144
	v_max_f32_e32 v145, 0xda24260, v145
	v_rcp_f32_e32 v144, v144
	v_rcp_f32_e32 v145, v145
	v_rcp_f32_e32 v152, v152
	v_pk_mul_f32 v[210:211], v[210:211], v[212:213]
	v_pk_mul_f32 v[144:145], v[144:145], v[146:147]
	s_nop 0
	v_pk_mul_f32 v[46:47], v[46:47], v[144:145]
	v_lshlrev_b32_e32 v144, 16, v140
	v_and_b32_e32 v140, 0xffff0000, v140
	v_lshlrev_b32_e32 v146, 16, v136
	v_and_b32_e32 v147, 0xffff0000, v136
	v_lshlrev_b32_e32 v136, 16, v141
	v_max_f32_e32 v140, 0xda24260, v140
	v_max_f32_e32 v136, 0xda24260, v136
	v_rcp_f32_e32 v145, v140
	v_rcp_f32_e32 v140, v136
	v_and_b32_e32 v136, 0xffff0000, v141
	v_max_f32_e32 v136, 0xda24260, v136
	v_rcp_f32_e32 v141, v136
	v_lshlrev_b32_e32 v136, 16, v137
	v_and_b32_e32 v137, 0xffff0000, v137
	v_pk_mul_f32 v[136:137], v[140:141], v[136:137]
	v_lshlrev_b32_e32 v140, 16, v138
	v_pk_mul_f32 v[50:51], v[50:51], v[136:137]
	v_lshlrev_b32_e32 v136, 16, v142
	v_and_b32_e32 v137, 0xffff0000, v142
	v_max_f32_e32 v136, 0xda24260, v136
	v_max_f32_e32 v137, 0xda24260, v137
	v_rcp_f32_e32 v136, v136
	v_rcp_f32_e32 v137, v137
	v_and_b32_e32 v141, 0xffff0000, v138
	v_lshlrev_b32_e32 v138, 16, v139
	v_and_b32_e32 v139, 0xffff0000, v139
	v_pk_mul_f32 v[136:137], v[136:137], v[140:141]
	v_max_f32_e32 v144, 0xda24260, v144
	v_pk_mul_f32 v[40:41], v[40:41], v[136:137]
	v_lshlrev_b32_e32 v136, 16, v143
	v_and_b32_e32 v137, 0xffff0000, v143
	v_max_f32_e32 v136, 0xda24260, v136
	v_max_f32_e32 v137, 0xda24260, v137
	v_rcp_f32_e32 v136, v136
	v_rcp_f32_e32 v137, v137
	v_rcp_f32_e32 v144, v144
	v_pk_mul_f32 v[152:153], v[152:153], v[154:155]
	v_pk_mul_f32 v[60:61], v[60:61], v[210:211]
	v_pk_mul_f32 v[136:137], v[136:137], v[138:139]
	v_lshlrev_b32_e32 v138, 16, v128
	v_pk_mul_f32 v[42:43], v[42:43], v[136:137]
	v_lshlrev_b32_e32 v136, 16, v132
	v_and_b32_e32 v132, 0xffff0000, v132
	v_and_b32_e32 v139, 0xffff0000, v128
	v_lshlrev_b32_e32 v128, 16, v133
	v_max_f32_e32 v132, 0xda24260, v132
	v_max_f32_e32 v128, 0xda24260, v128
	v_rcp_f32_e32 v137, v132
	v_rcp_f32_e32 v132, v128
	v_and_b32_e32 v128, 0xffff0000, v133
	v_max_f32_e32 v128, 0xda24260, v128
	v_rcp_f32_e32 v133, v128
	v_lshlrev_b32_e32 v128, 16, v129
	v_and_b32_e32 v129, 0xffff0000, v129
	v_pk_mul_f32 v[128:129], v[132:133], v[128:129]
	v_lshlrev_b32_e32 v132, 16, v130
	v_pk_mul_f32 v[38:39], v[38:39], v[128:129]
	v_lshlrev_b32_e32 v128, 16, v134
	v_and_b32_e32 v129, 0xffff0000, v134
	v_max_f32_e32 v128, 0xda24260, v128
	v_max_f32_e32 v129, 0xda24260, v129
	v_rcp_f32_e32 v128, v128
	v_rcp_f32_e32 v129, v129
	v_and_b32_e32 v133, 0xffff0000, v130
	v_lshlrev_b32_e32 v130, 16, v131
	v_and_b32_e32 v131, 0xffff0000, v131
	v_pk_mul_f32 v[128:129], v[128:129], v[132:133]
	v_max_f32_e32 v136, 0xda24260, v136
	v_pk_mul_f32 v[28:29], v[28:29], v[128:129]
	v_lshlrev_b32_e32 v128, 16, v135
	v_and_b32_e32 v129, 0xffff0000, v135
	v_max_f32_e32 v128, 0xda24260, v128
	v_max_f32_e32 v129, 0xda24260, v129
	v_rcp_f32_e32 v128, v128
	v_rcp_f32_e32 v129, v129
	v_rcp_f32_e32 v136, v136
	v_pk_mul_f32 v[144:145], v[144:145], v[146:147]
	v_pk_mul_f32 v[52:53], v[52:53], v[152:153]
	v_pk_mul_f32 v[128:129], v[128:129], v[130:131]
	s_waitcnt vmcnt(0)
	v_lshlrev_b32_e32 v130, 16, v184
	v_pk_mul_f32 v[30:31], v[30:31], v[128:129]
	v_lshlrev_b32_e32 v128, 16, v188
	v_and_b32_e32 v129, 0xffff0000, v188
	v_max_f32_e32 v128, 0xda24260, v128
	v_max_f32_e32 v129, 0xda24260, v129
	v_rcp_f32_e32 v128, v128
	v_rcp_f32_e32 v129, v129
	v_and_b32_e32 v131, 0xffff0000, v184
	v_pk_mul_f32 v[136:137], v[136:137], v[138:139]
	v_pk_mul_f32 v[48:49], v[48:49], v[144:145]
	v_pk_mul_f32 v[128:129], v[128:129], v[130:131]
	v_lshlrev_b32_e32 v130, 16, v185
	v_pk_mul_f32 v[32:33], v[32:33], v[128:129]
	v_lshlrev_b32_e32 v128, 16, v189
	v_and_b32_e32 v129, 0xffff0000, v189
	v_max_f32_e32 v128, 0xda24260, v128
	v_max_f32_e32 v129, 0xda24260, v129
	v_rcp_f32_e32 v128, v128
	v_rcp_f32_e32 v129, v129
	v_and_b32_e32 v131, 0xffff0000, v185
	v_pk_mul_f32 v[36:37], v[36:37], v[136:137]
	v_pk_mul_f32 v[128:129], v[128:129], v[130:131]
	s_nop 0
	v_pk_mul_f32 v[34:35], v[34:35], v[128:129]
	v_lshlrev_b32_e32 v128, 16, v190
	v_and_b32_e32 v129, 0xffff0000, v190
	v_max_f32_e32 v128, 0xda24260, v128
	v_max_f32_e32 v129, 0xda24260, v129
	v_rcp_f32_e32 v128, v128
	v_rcp_f32_e32 v129, v129
	v_lshlrev_b32_e32 v130, 16, v186
	v_and_b32_e32 v131, 0xffff0000, v186
	v_pk_mul_f32 v[128:129], v[128:129], v[130:131]
	s_nop 0
	v_pk_mul_f32 v[24:25], v[24:25], v[128:129]
	v_lshlrev_b32_e32 v128, 16, v191
	v_and_b32_e32 v129, 0xffff0000, v191
	v_max_f32_e32 v128, 0xda24260, v128
	v_max_f32_e32 v129, 0xda24260, v129
	v_rcp_f32_e32 v128, v128
	v_rcp_f32_e32 v129, v129
	v_lshlrev_b32_e32 v130, 16, v187
	v_and_b32_e32 v131, 0xffff0000, v187
	v_pk_mul_f32 v[128:129], v[128:129], v[130:131]
	s_nop 0
	v_pk_mul_f32 v[26:27], v[26:27], v[128:129]
	v_lshlrev_b32_e32 v128, 16, v180
	v_and_b32_e32 v129, 0xffff0000, v180
	v_max_f32_e32 v128, 0xda24260, v128
	v_max_f32_e32 v129, 0xda24260, v129
	v_rcp_f32_e32 v128, v128
	v_rcp_f32_e32 v129, v129
	v_lshlrev_b32_e32 v130, 16, v176
	v_and_b32_e32 v131, 0xffff0000, v176
	v_pk_mul_f32 v[128:129], v[128:129], v[130:131]
	s_nop 0
	v_pk_mul_f32 v[20:21], v[20:21], v[128:129]
	v_lshlrev_b32_e32 v128, 16, v181
	v_and_b32_e32 v129, 0xffff0000, v181
	v_max_f32_e32 v128, 0xda24260, v128
	v_max_f32_e32 v129, 0xda24260, v129
	v_rcp_f32_e32 v128, v128
	v_rcp_f32_e32 v129, v129
	v_lshlrev_b32_e32 v130, 16, v177
	v_and_b32_e32 v131, 0xffff0000, v177
	v_pk_mul_f32 v[128:129], v[128:129], v[130:131]
	s_nop 0
	v_pk_mul_f32 v[22:23], v[22:23], v[128:129]
	v_lshlrev_b32_e32 v128, 16, v182
	v_and_b32_e32 v129, 0xffff0000, v182
	v_max_f32_e32 v128, 0xda24260, v128
	v_max_f32_e32 v129, 0xda24260, v129
	v_rcp_f32_e32 v128, v128
	v_rcp_f32_e32 v129, v129
	v_lshlrev_b32_e32 v130, 16, v178
	v_and_b32_e32 v131, 0xffff0000, v178
	v_pk_mul_f32 v[128:129], v[128:129], v[130:131]
	s_nop 0
	v_pk_mul_f32 v[12:13], v[12:13], v[128:129]
	v_lshlrev_b32_e32 v128, 16, v183
	v_and_b32_e32 v129, 0xffff0000, v183
	v_max_f32_e32 v128, 0xda24260, v128
	v_max_f32_e32 v129, 0xda24260, v129
	v_rcp_f32_e32 v128, v128
	v_rcp_f32_e32 v129, v129
	v_lshlrev_b32_e32 v130, 16, v179
	v_and_b32_e32 v131, 0xffff0000, v179
	v_pk_mul_f32 v[128:129], v[128:129], v[130:131]
	s_nop 0
	v_pk_mul_f32 v[14:15], v[14:15], v[128:129]
	v_lshlrev_b32_e32 v128, 16, v172
	v_and_b32_e32 v129, 0xffff0000, v172
	v_max_f32_e32 v128, 0xda24260, v128
	v_max_f32_e32 v129, 0xda24260, v129
	v_rcp_f32_e32 v128, v128
	v_rcp_f32_e32 v129, v129
	v_lshlrev_b32_e32 v130, 16, v168
	v_and_b32_e32 v131, 0xffff0000, v168
	v_pk_mul_f32 v[128:129], v[128:129], v[130:131]
	s_nop 0
	v_pk_mul_f32 v[16:17], v[16:17], v[128:129]
	v_lshlrev_b32_e32 v128, 16, v173
	v_and_b32_e32 v129, 0xffff0000, v173
	v_max_f32_e32 v128, 0xda24260, v128
	v_max_f32_e32 v129, 0xda24260, v129
	v_rcp_f32_e32 v128, v128
	v_rcp_f32_e32 v129, v129
	v_lshlrev_b32_e32 v130, 16, v169
	v_and_b32_e32 v131, 0xffff0000, v169
	v_pk_mul_f32 v[128:129], v[128:129], v[130:131]
	s_nop 0
	v_pk_mul_f32 v[18:19], v[18:19], v[128:129]
	v_lshlrev_b32_e32 v128, 16, v174
	v_and_b32_e32 v129, 0xffff0000, v174
	v_max_f32_e32 v128, 0xda24260, v128
	v_max_f32_e32 v129, 0xda24260, v129
	v_rcp_f32_e32 v128, v128
	v_rcp_f32_e32 v129, v129
	v_lshlrev_b32_e32 v130, 16, v170
	v_and_b32_e32 v131, 0xffff0000, v170
	v_pk_mul_f32 v[128:129], v[128:129], v[130:131]
	s_nop 0
	v_pk_mul_f32 v[8:9], v[8:9], v[128:129]
	v_lshlrev_b32_e32 v128, 16, v175
	v_and_b32_e32 v129, 0xffff0000, v175
	v_max_f32_e32 v128, 0xda24260, v128
	v_max_f32_e32 v129, 0xda24260, v129
	v_rcp_f32_e32 v128, v128
	v_rcp_f32_e32 v129, v129
	v_lshlrev_b32_e32 v130, 16, v171
	v_and_b32_e32 v131, 0xffff0000, v171
	v_pk_mul_f32 v[128:129], v[128:129], v[130:131]
	s_nop 0
	v_pk_mul_f32 v[10:11], v[10:11], v[128:129]
	v_lshlrev_b32_e32 v128, 16, v164
	v_and_b32_e32 v129, 0xffff0000, v164
	v_max_f32_e32 v128, 0xda24260, v128
	v_max_f32_e32 v129, 0xda24260, v129
	v_rcp_f32_e32 v128, v128
	v_rcp_f32_e32 v129, v129
	v_lshlrev_b32_e32 v130, 16, v160
	v_and_b32_e32 v131, 0xffff0000, v160
	v_pk_mul_f32 v[128:129], v[128:129], v[130:131]
	s_nop 0
	v_pk_mul_f32 v[4:5], v[4:5], v[128:129]
	v_lshlrev_b32_e32 v128, 16, v165
	v_and_b32_e32 v129, 0xffff0000, v165
	v_max_f32_e32 v128, 0xda24260, v128
	v_max_f32_e32 v129, 0xda24260, v129
	v_rcp_f32_e32 v128, v128
	v_rcp_f32_e32 v129, v129
	v_lshlrev_b32_e32 v130, 16, v161
	v_and_b32_e32 v131, 0xffff0000, v161
	v_pk_mul_f32 v[128:129], v[128:129], v[130:131]
	s_nop 0
	v_pk_mul_f32 v[6:7], v[6:7], v[128:129]
	v_lshlrev_b32_e32 v128, 16, v166
	v_and_b32_e32 v129, 0xffff0000, v166
	v_max_f32_e32 v128, 0xda24260, v128
	v_max_f32_e32 v129, 0xda24260, v129
	v_rcp_f32_e32 v128, v128
	v_rcp_f32_e32 v129, v129
	v_lshlrev_b32_e32 v130, 16, v162
	v_and_b32_e32 v131, 0xffff0000, v162
	v_pk_mul_f32 v[128:129], v[128:129], v[130:131]
	s_nop 0
	v_pk_mul_f32 v[0:1], v[0:1], v[128:129]
	v_lshlrev_b32_e32 v128, 16, v167
	v_and_b32_e32 v129, 0xffff0000, v167
	v_max_f32_e32 v128, 0xda24260, v128
	v_max_f32_e32 v129, 0xda24260, v129
	v_rcp_f32_e32 v128, v128
	v_rcp_f32_e32 v129, v129
	v_lshlrev_b32_e32 v130, 16, v163
	v_and_b32_e32 v131, 0xffff0000, v163
	v_pk_mul_f32 v[128:129], v[128:129], v[130:131]
	s_nop 0
	v_pk_mul_f32 v[2:3], v[2:3], v[128:129]
	s_branch .LBB0_1580
